# previous best + S5 prompt recurrence steps fused into four FMAs each (30 fewer dependent VALU ops per sub-chunk)
# baseline (speedup 1.0000x reference)
; DEVINL f32x4 mfma16(bf16x8 a, bf16x8 b, f32x4 c) { return __builtin_amdgcn_mfma_f32_16x16x32_bf16(a, b, c, 0, 0, 0); }
; DEVINL void s5_seg(const Params& p, char* wsm, int rb, int ntok, int g, float& hr, float& hi, bool outp) {
;     ...
;     for (int nf = 0; nf < 8; ++nf) {
;       f32x4 c = mfma16(a, bb[nf], f32x4{0, 0, 0, 0});
; #pragma unroll
;       for (int j = 0; j < 4; ++j) BUs[((lane >> 4) * 4 + j) * 132 + nf * 16 + (lane & 15)] = c[j];
;     }
;     __builtin_amdgcn_wave_barrier();
;     asm volatile("s_waitcnt lgkmcnt(0)" ::: "memory");
;     if (nt == 16) {
;       float2 bu[16];
; #pragma unroll
;       for (int t = 0; t < 16; ++t) bu[t] = *(const float2*)(BUs + t * 132 + 2 * lane);
; #pragma unroll
;       for (int t = 0; t < 16; ++t) {
;         float nr = ab.x * hr - ab.y * hi + bu[t].x;
;         float ni = ab.x * hi + ab.y * hr + bu[t].y;
;         hr = nr; hi = ni;
;         if (outp) *(unsigned*)(Hs + t * 136 + 2 * lane) = pack2(hr, hi);
;       }
;     } else {
;       for (int t = 0; t < nt; ++t) {
;         float2 bu = *(const float2*)(BUs + t * 132 + 2 * lane);
;         float nr = ab.x * hr - ab.y * hi + bu.x;
;         float ni = ab.x * hi + ab.y * hr + bu.y;
;         hr = nr; hi = ni;
;         if (outp) *(unsigned*)(Hs + t * 136 + 2 * lane) = pack2(hr, hi);
;       }
;     }
;     __builtin_amdgcn_wave_barrier();
;     asm volatile("s_waitcnt lgkmcnt(0)" ::: "memory");
;     if (outp) {
;       f32x4 y = f32x4{0, 0, 0, 0};
; #pragma unroll
;       for (int ks = 0; ks < 4; ++ks) {
;         bf16x8 ha = *(const bf16x8*)(Hs + (lane & 15) * 136 + ks * 32 + 8 * (lane >> 4));
;         y = mfma16(ha, cm[ks], y);
;       }
.LBB0_475:
	s_or_b64 exec, exec, s[0:1]
	s_movk_i32 s0, 0x3200
	v_mul_lo_u32 v61, v70, s0
	v_mul_u32_u24_e32 v76, 0x110, v73
	v_and_b32_e32 v77, 48, v64
	s_movk_i32 s0, 0x840
	s_waitcnt vmcnt(0)
	v_mfma_f32_16x16x32_bf16 v[20:23], v[52:55], v[20:23], 0
	v_lshl_or_b32 v70, v72, 3, v61
	v_add3_u32 v76, v61, v76, v77
	v_mad_u32_u24 v61, v74, s0, v61
	v_mfma_f32_16x16x32_bf16 v[12:15], v[52:55], v[12:15], 0
	v_lshl_or_b32 v61, v73, 2, v61
	v_add_u32_e32 v73, 0x400, v61
	s_nop 5
	ds_write2_b32 v61, v20, v12 offset1:16
	ds_write2_b32 v61, v21, v13 offset0:132 offset1:148
	ds_write2_b32 v73, v22, v14 offset0:8 offset1:24
	ds_write2_b32 v73, v23, v15 offset0:140 offset1:156
	v_mfma_f32_16x16x32_bf16 v[12:15], v[52:55], v[32:35], 0
	v_lshlrev_b32_e32 v72, 2, v72
	v_sub_u32_e32 v72, v70, v72
	v_mfma_f32_16x16x32_bf16 v[20:23], v[52:55], v[28:31], 0
	s_nop 7
	ds_write2_b32 v61, v12, v20 offset0:32 offset1:48
	ds_write2_b32 v61, v13, v21 offset0:164 offset1:180
	ds_write2_b32 v73, v14, v22 offset0:40 offset1:56
	ds_write2_b32 v73, v15, v23 offset0:172 offset1:188
	v_mfma_f32_16x16x32_bf16 v[12:15], v[52:55], v[40:43], 0
	v_mfma_f32_16x16x32_bf16 v[20:23], v[52:55], v[36:39], 0
	s_nop 7
	ds_write2_b32 v61, v12, v20 offset0:64 offset1:80
	ds_write2_b32 v61, v13, v21 offset0:196 offset1:212
	ds_write2_b32 v73, v14, v22 offset0:72 offset1:88
	ds_write2_b32 v73, v15, v23 offset0:204 offset1:220
	v_mfma_f32_16x16x32_bf16 v[12:15], v[52:55], v[48:51], 0
	v_mfma_f32_16x16x32_bf16 v[20:23], v[52:55], v[44:47], 0
	s_nop 7
	ds_write2_b32 v61, v12, v20 offset0:96 offset1:112
	ds_write2_b32 v61, v13, v21 offset0:228 offset1:244
	ds_write2_b32 v73, v14, v22 offset0:104 offset1:120
	ds_write2_b32 v73, v15, v23 offset0:236 offset1:252
	s_waitcnt lgkmcnt(0)
	ds_read_b64 v[12:13], v70
	v_mul_f32_e32 v14, v66, v59
	v_fma_f32 v14, v65, v58, -v14
	s_waitcnt lgkmcnt(0)
	v_add_f32_e32 v14, v14, v12
	v_mul_f32_e32 v12, v65, v59
	v_fmac_f32_e32 v12, v66, v58
	v_add_f32_e32 v15, v12, v13
	v_add_u32_e32 v12, 0x8000, v15
	v_add_u32_e32 v13, 0x8000, v14
	v_perm_b32 v12, v12, v13, s25
	ds_write_b32 v72, v12 offset:8448
	ds_read_b64 v[12:13], v70 offset:528
	v_mul_f32_e32 v20, v59, v15
	v_fma_f32 v20, v58, v14, -v20
	s_waitcnt lgkmcnt(0)
	v_add_f32_e32 v20, v12, v20
	v_mul_f32_e32 v12, v58, v15
	v_fmac_f32_e32 v12, v59, v14
	v_add_f32_e32 v14, v12, v13
	v_add_u32_e32 v12, 0x8000, v14
	v_add_u32_e32 v13, 0x8000, v20
	v_perm_b32 v12, v12, v13, s25
	ds_write_b32 v72, v12 offset:8720
	ds_read_b64 v[12:13], v70 offset:1056
	v_mul_f32_e32 v15, v59, v14
	v_fma_f32 v15, v58, v20, -v15
	s_waitcnt lgkmcnt(0)
	v_add_f32_e32 v15, v12, v15
	v_mul_f32_e32 v12, v58, v14
	v_fmac_f32_e32 v12, v59, v20
	v_add_f32_e32 v14, v12, v13
	v_add_u32_e32 v12, 0x8000, v14
	v_add_u32_e32 v13, 0x8000, v15
	v_perm_b32 v12, v12, v13, s25
	ds_write_b32 v72, v12 offset:8992
	ds_read_b64 v[12:13], v70 offset:1584
	v_mul_f32_e32 v20, v59, v14
	v_fma_f32 v20, v58, v15, -v20
	s_waitcnt lgkmcnt(0)
	v_add_f32_e32 v20, v12, v20
	v_mul_f32_e32 v12, v58, v14
	v_fmac_f32_e32 v12, v59, v15
	v_add_f32_e32 v14, v12, v13
	v_add_u32_e32 v12, 0x8000, v14
	v_add_u32_e32 v13, 0x8000, v20
	v_perm_b32 v12, v12, v13, s25
	ds_write_b32 v72, v12 offset:9264
	ds_read_b64 v[12:13], v70 offset:2112
	v_mul_f32_e32 v15, v59, v14
	v_fma_f32 v15, v58, v20, -v15
	s_waitcnt lgkmcnt(0)
	v_add_f32_e32 v15, v12, v15
	v_mul_f32_e32 v12, v58, v14
	v_fmac_f32_e32 v12, v59, v20
	v_add_f32_e32 v14, v12, v13
	v_add_u32_e32 v12, 0x8000, v14
	v_add_u32_e32 v13, 0x8000, v15
	v_perm_b32 v12, v12, v13, s25
	ds_write_b32 v72, v12 offset:9536
	ds_read_b64 v[12:13], v70 offset:2640
	v_mul_f32_e32 v20, v59, v14
	v_fma_f32 v20, v58, v15, -v20
	s_waitcnt lgkmcnt(0)
	v_add_f32_e32 v20, v12, v20
	v_mul_f32_e32 v12, v58, v14
	v_fmac_f32_e32 v12, v59, v15
	v_add_f32_e32 v14, v12, v13
	v_add_u32_e32 v12, 0x8000, v14
	v_add_u32_e32 v13, 0x8000, v20
	v_perm_b32 v12, v12, v13, s25
	ds_write_b32 v72, v12 offset:9808
	ds_read_b64 v[12:13], v70 offset:3168
	s_waitcnt lgkmcnt(0)
	v_fma_f32 v12, -v59, v14, v12
	v_fma_f32 v12, v58, v20, v12
	v_fma_f32 v20, v59, v20, v13
	v_fma_f32 v20, v58, v14, v20
	v_add_u32_e32 v13, 0x8000, v20
	v_add_u32_e32 v14, 0x8000, v12
	v_perm_b32 v13, v13, v14, s25
	ds_write_b32 v72, v13 offset:10080
	ds_read_b64 v[14:15], v70 offset:3696
	v_mul_f32_e32 v13, v59, v20
	v_fma_f32 v13, v58, v12, -v13
	s_waitcnt lgkmcnt(0)
	v_add_f32_e32 v13, v14, v13
	v_mul_f32_e32 v14, v58, v20
	v_fmac_f32_e32 v14, v59, v12
	v_add_f32_e32 v12, v14, v15
	v_add_u32_e32 v14, 0x8000, v12
	v_add_u32_e32 v15, 0x8000, v13
	v_perm_b32 v14, v14, v15, s25
	ds_write_b32 v72, v14 offset:10352
	s_waitcnt lgkmcnt(0)
	ds_read_b128 v[20:23], v76 offset:8448
	s_waitcnt lgkmcnt(0)
	v_mfma_f32_16x16x32_bf16 v[20:23], v[20:23], v[24:27], 0
	ds_read_b128 v[24:27], v76 offset:8512
	s_waitcnt lgkmcnt(0)
	v_mfma_f32_16x16x32_bf16 v[14:17], v[24:27], v[16:19], v[20:23]
	s_nop 4
	ds_read_b128 v[18:21], v76 offset:8576
	s_waitcnt lgkmcnt(0)
	v_mfma_f32_16x16x32_bf16 v[8:11], v[18:21], v[8:11], v[14:17]
	s_nop 2
	ds_read_b128 v[14:17], v76 offset:8640
	s_waitcnt lgkmcnt(0)
	v_mfma_f32_16x16x32_bf16 v[4:7], v[14:17], v[4:7], v[8:11]
	s_and_saveexec_b64 s[34:35], vcc
	s_cbranch_execz .LBB0_477
; DEVINL float bf2f(u16 h) { return __uint_as_float(((unsigned)h) << 16); }
; DEVINL float lane_xor1(float v) { return dpp_f<0xB1>(v); }
; DEVINL void store_pairs(u16* base, size_t ld, int rb, int col, float v0, float v1, float v2, float v3) {
;   const float p0 = lane_xor1(v0), p1 = lane_xor1(v1), p2 = lane_xor1(v2), p3 = lane_xor1(v3);
;   const bool odd = (col & 1) != 0;
;   const int r0 = odd ? rb + 2 : rb, c0 = col & ~1;
;   const unsigned w0 = odd ? pack2(p2, v2) : pack2(v0, p0);
;   const unsigned w1 = odd ? pack2(p3, v3) : pack2(v1, p1);
;   *(unsigned*)(base + (size_t)r0 * ld + c0) = w0;
;   *(unsigned*)(base + (size_t)(r0 + 1) * ld + c0) = w1;
; }
; DEVINL void s5_seg(const Params& p, char* wsm, int rb, int ntok, int g, float& hr, float& hi, bool outp) {
;     ...
;       if (tk0 < nt) {
;         float yv[4];
; #pragma unroll
;         for (int j = 0; j < 4; ++j) yv[j] = geluf_(y[j] + dsk * bf2f(u_cur[j]));
;         store_pairs(yg, 512, rb + t0 + tk0, ucol, yv[0], yv[1], yv[2], yv[3]);
	s_nop 5
	v_fma_f32 v4, v67, v68, v4
	v_mul_f32_e32 v9, 0x3d372713, v4
	v_mul_f32_e32 v9, v4, v9
	v_fma_f32 v5, v67, v71, v5
	v_fma_f32 v9, v4, v9, v4
	v_mul_f32_e32 v14, 0x3d372713, v5
	v_mul_f32_e32 v9, 0x3f4c422a, v9
	v_mul_f32_e32 v14, v5, v14
	v_add_f32_e32 v9, v9, v9
	v_fma_f32 v14, v5, v14, v5
	v_mul_f32_e32 v9, 0x3fb8aa3b, v9
	v_mul_f32_e32 v14, 0x3f4c422a, v14
	v_exp_f32_e32 v10, v9
	v_add_f32_e32 v14, v14, v14
	v_fma_f32 v6, v67, v69, v6
	v_mul_f32_e32 v14, 0x3fb8aa3b, v14
	v_mul_f32_e32 v15, 0x3d372713, v6
	v_exp_f32_e32 v14, v14
	v_mul_f32_e32 v15, v6, v15
	v_fma_f32 v15, v6, v15, v6
	v_add_f32_e32 v10, 1.0, v10
	v_mul_f32_e32 v15, 0x3f4c422a, v15
	v_rcp_f32_e32 v10, v10
	v_add_f32_e32 v15, v15, v15
	v_add_f32_e32 v14, 1.0, v14
	v_mul_f32_e32 v15, 0x3fb8aa3b, v15
	v_rcp_f32_e32 v14, v14
	v_exp_f32_e32 v15, v15
	v_fma_f32 v10, v10, -2.0, 1.0
	v_mul_f32_e32 v4, 0.5, v4
	v_add_f32_e32 v10, 1.0, v10
	v_fmac_f32_e32 v7, v67, v63
	v_mul_f32_e32 v4, v4, v10
	v_fma_f32 v10, v14, -2.0, 1.0
	v_add_f32_e32 v14, 1.0, v15
	v_mul_f32_e32 v15, 0x3d372713, v7
	v_mul_f32_e32 v15, v7, v15
	v_fma_f32 v15, v7, v15, v7
	v_mul_f32_e32 v15, 0x3f4c422a, v15
	v_add_f32_e32 v15, v15, v15
	v_mul_f32_e32 v15, 0x3fb8aa3b, v15
	v_rcp_f32_e32 v14, v14
	v_exp_f32_e32 v15, v15
	v_mul_f32_e32 v5, 0.5, v5
	v_add_f32_e32 v10, 1.0, v10
	v_mul_f32_e32 v5, v5, v10
	v_fma_f32 v10, v14, -2.0, 1.0
	v_add_f32_e32 v14, 1.0, v15
	v_rcp_f32_e32 v14, v14
	v_mul_f32_e32 v6, 0.5, v6
	v_add_f32_e32 v10, 1.0, v10
	v_mul_f32_e32 v6, v6, v10
	v_fma_f32 v10, v14, -2.0, 1.0
	v_and_b32_e32 v11, 1, v64
	v_mul_f32_e32 v7, 0.5, v7
	v_add_f32_e32 v10, 1.0, v10
	v_mul_f32_e32 v7, v7, v10
	v_mov_b32_dpp v15, v6 quad_perm:[1,0,3,2] row_mask:0xf bank_mask:0xf bound_ctrl:1
	v_mov_b32_dpp v10, v4 quad_perm:[1,0,3,2] row_mask:0xf bank_mask:0xf bound_ctrl:1
	v_cmp_eq_u32_e32 vcc, 0, v11
	v_mov_b32_dpp v14, v5 quad_perm:[1,0,3,2] row_mask:0xf bank_mask:0xf bound_ctrl:1
	v_mov_b32_dpp v16, v7 quad_perm:[1,0,3,2] row_mask:0xf bank_mask:0xf bound_ctrl:1
	v_cndmask_b32_e32 v6, v6, v10, vcc
	v_cndmask_b32_e32 v4, v15, v4, vcc
	v_add_u32_e32 v6, 0x8000, v6
	v_add_u32_e32 v4, 0x8000, v4
	v_perm_b32 v6, v6, v4, s25
	v_cndmask_b32_e32 v4, v7, v14, vcc
	v_cndmask_b32_e32 v5, v16, v5, vcc
	v_and_b32_e32 v8, -2, v60
	v_readlane_b32 s0, v194, 29
	v_add_u32_e32 v4, 0x8000, v4
	v_add_u32_e32 v5, 0x8000, v5
	v_ashrrev_i32_e32 v9, 31, v8
	v_readlane_b32 s1, v194, 30
	v_perm_b32 v7, v4, v5, s25
	v_lshlrev_b32_e32 v4, 11, v11
	v_lshl_add_u64 v[8:9], v[8:9], 1, s[0:1]
	v_lshl_or_b32 v4, v62, 10, v4
	v_mov_b32_e32 v5, v2
	v_lshl_add_u64 v[4:5], v[8:9], 0, v[4:5]
	global_store_dword v[4:5], v6, off
	global_store_dword v[4:5], v7, off offset:1024

; DEVINL f32x4 mfma16(bf16x8 a, bf16x8 b, f32x4 c) { return __builtin_amdgcn_mfma_f32_16x16x32_bf16(a, b, c, 0, 0, 0); }
; DEVINL void s5_seg(const Params& p, char* wsm, int rb, int ntok, int g, float& hr, float& hi, bool outp) {
;     ...
;     for (int nf = 0; nf < 8; ++nf) {
;       f32x4 c = mfma16(a, bb[nf], f32x4{0, 0, 0, 0});
; #pragma unroll
;       for (int j = 0; j < 4; ++j) BUs[((lane >> 4) * 4 + j) * 132 + nf * 16 + (lane & 15)] = c[j];
;     }
;     __builtin_amdgcn_wave_barrier();
;     asm volatile("s_waitcnt lgkmcnt(0)" ::: "memory");
;     if (nt == 16) {
;       float2 bu[16];
; #pragma unroll
;       for (int t = 0; t < 16; ++t) bu[t] = *(const float2*)(BUs + t * 132 + 2 * lane);
; #pragma unroll
;       for (int t = 0; t < 16; ++t) {
;         float nr = ab.x * hr - ab.y * hi + bu[t].x;
;         float ni = ab.x * hi + ab.y * hr + bu[t].y;
;         hr = nr; hi = ni;
;         if (outp) *(unsigned*)(Hs + t * 136 + 2 * lane) = pack2(hr, hi);
.LBB0_527:
	s_or_b64 exec, exec, s[46:47]
	v_mfma_f32_16x16x32_bf16 v[110:113], v[58:61], v[10:13], 0
	v_add_u32_e32 v131, 0x400, v87
	v_pk_mul_f32 v[154:155], v[64:65], v[66:67]
	v_mul_f32_e32 v66, v74, v66
	v_mfma_f32_16x16x32_bf16 v[132:135], v[58:61], v[6:9], 0
	v_fmac_f32_e32 v66, v64, v67
	s_and_b64 s[0:1], exec, s[36:37]
	s_or_b64 s[44:45], s[0:1], s[44:45]
	v_mfma_f32_16x16x32_bf16 v[136:139], v[58:61], v[18:21], 0
	v_mfma_f32_16x16x32_bf16 v[140:143], v[58:61], v[14:17], 0
	s_nop 2
	ds_write2_b32 v87, v110, v132 offset1:16
	ds_write2_b32 v87, v111, v133 offset0:132 offset1:148
	ds_write2_b32 v131, v112, v134 offset0:8 offset1:24
	v_mfma_f32_16x16x32_bf16 v[144:147], v[58:61], v[26:29], 0
	ds_write2_b32 v131, v113, v135 offset0:140 offset1:156
	ds_write2_b32 v87, v136, v140 offset0:32 offset1:48
	ds_write2_b32 v87, v137, v141 offset0:164 offset1:180
	v_mfma_f32_16x16x32_bf16 v[110:113], v[58:61], v[22:25], 0
	ds_write2_b32 v131, v138, v142 offset0:40 offset1:56
	ds_write2_b32 v131, v139, v143 offset0:172 offset1:188
	s_nop 5
	ds_write2_b32 v87, v144, v110 offset0:64 offset1:80
	ds_write2_b32 v87, v145, v111 offset0:196 offset1:212
	ds_write2_b32 v131, v146, v112 offset0:72 offset1:88
	ds_write2_b32 v131, v147, v113 offset0:204 offset1:220
	v_mfma_f32_16x16x32_bf16 v[132:135], v[58:61], v[34:37], 0
	v_mfma_f32_16x16x32_bf16 v[58:61], v[58:61], v[30:33], 0
	s_nop 7
	ds_write2_b32 v87, v132, v58 offset0:96 offset1:112
	ds_write2_b32 v87, v133, v59 offset0:228 offset1:244
	ds_write2_b32 v131, v134, v60 offset0:104 offset1:120
	ds_write2_b32 v131, v135, v61 offset0:236 offset1:252
	s_waitcnt lgkmcnt(0)
	ds_read2_b64 v[58:61], v85 offset1:66
	ds_read2_b64 v[110:113], v85 offset0:132 offset1:198
	v_add_u32_e32 v131, 0x800, v85
	ds_read2_b64 v[132:135], v131 offset0:8 offset1:74
	ds_read2_b64 v[136:139], v131 offset0:140 offset1:206
	v_add_u32_e32 v131, 0x1000, v85
	ds_read2_b64 v[140:143], v131 offset0:16 offset1:82
	ds_read2_b64 v[144:147], v131 offset0:148 offset1:214
	v_add_u32_e32 v131, 0x1800, v85
	ds_read2_b64 v[148:151], v131 offset0:24 offset1:90
	ds_read_b64 v[152:153], v85 offset:7392
	v_sub_f32_e32 v131, v154, v155
	s_waitcnt lgkmcnt(7)
	v_add_f32_e32 v58, v131, v58
	v_add_f32_e32 v59, v66, v59
	v_add_u32_e32 v66, 0x8000, v59
	v_add_u32_e32 v67, 0x8000, v58
	v_perm_b32 v66, v66, v67, s25
	v_fma_f32 v60, -v65, v59, v60
	v_fma_f32 v60, v64, v58, v60
	v_fma_f32 v58, v65, v58, v61
	v_fma_f32 v58, v64, v59, v58
	v_add_u32_e32 v59, 0x8000, v58
	v_add_u32_e32 v61, 0x8000, v60
	v_perm_b32 v59, v59, v61, s25
	v_add_u32_e32 v61, 0x2000, v106
	ds_write2_b32 v61, v66, v59 offset0:64 offset1:132
	s_waitcnt lgkmcnt(7)
	v_fma_f32 v59, -v65, v58, v110
	v_fma_f32 v59, v64, v60, v59
	v_fma_f32 v58, v64, v58, v111
	v_fma_f32 v58, v65, v60, v58
	v_add_u32_e32 v60, 0x8000, v58
	v_add_u32_e32 v61, 0x8000, v59
	v_perm_b32 v60, v60, v61, s25
	v_fma_f32 v61, -v65, v58, v112
	v_fma_f32 v61, v64, v59, v61
	v_fma_f32 v58, v64, v58, v113
	v_fma_f32 v58, v65, v59, v58
	v_add_u32_e32 v59, 0x8000, v58
	v_add_u32_e32 v66, 0x8000, v61
	v_perm_b32 v59, v59, v66, s25
	v_add_u32_e32 v66, 0x2200, v106
	ds_write2_b32 v66, v60, v59 offset0:72 offset1:140
	s_waitcnt lgkmcnt(7)
	v_fma_f32 v59, -v65, v58, v132
	v_fma_f32 v59, v64, v61, v59
	v_fma_f32 v58, v64, v58, v133
	v_fma_f32 v58, v65, v61, v58
	v_add_u32_e32 v60, 0x8000, v58
	v_add_u32_e32 v61, 0x8000, v59
	v_perm_b32 v60, v60, v61, s25
	v_fma_f32 v61, -v65, v58, v134
	v_fma_f32 v61, v64, v59, v61
	v_fma_f32 v58, v64, v58, v135
	v_fma_f32 v58, v65, v59, v58
	v_add_u32_e32 v59, 0x8000, v58
	v_add_u32_e32 v66, 0x8000, v61
	v_perm_b32 v59, v59, v66, s25
	v_add_u32_e32 v66, 0x2400, v106
	ds_write2_b32 v66, v60, v59 offset0:80 offset1:148
	s_waitcnt lgkmcnt(7)
	v_fma_f32 v59, -v65, v58, v136
	v_fma_f32 v59, v64, v61, v59
	v_fma_f32 v58, v64, v58, v137
	v_fma_f32 v58, v65, v61, v58
	v_add_u32_e32 v60, 0x8000, v58
	v_add_u32_e32 v61, 0x8000, v59
	v_perm_b32 v60, v60, v61, s25
	v_fma_f32 v61, -v65, v58, v138
	v_fma_f32 v61, v64, v59, v61
	v_fma_f32 v58, v64, v58, v139
	v_fma_f32 v58, v65, v59, v58
	v_add_u32_e32 v59, 0x8000, v58
	v_add_u32_e32 v66, 0x8000, v61
	v_perm_b32 v59, v59, v66, s25
	v_add_u32_e32 v66, 0x2600, v106
	ds_write2_b32 v66, v60, v59 offset0:88 offset1:156
	s_waitcnt lgkmcnt(7)
	v_fma_f32 v59, -v65, v58, v140
	v_fma_f32 v59, v64, v61, v59
	v_fma_f32 v58, v64, v58, v141
	v_fma_f32 v58, v65, v61, v58
	v_add_u32_e32 v60, 0x8000, v58
	v_add_u32_e32 v61, 0x8000, v59
	v_perm_b32 v60, v60, v61, s25
	v_fma_f32 v61, -v65, v58, v142
	v_fma_f32 v61, v64, v59, v61
	v_fma_f32 v58, v64, v58, v143
	v_fma_f32 v58, v65, v59, v58
	v_add_u32_e32 v59, 0x8000, v58
	v_add_u32_e32 v66, 0x8000, v61
	v_perm_b32 v59, v59, v66, s25
	v_add_u32_e32 v66, 0x2800, v106
	ds_write2_b32 v66, v60, v59 offset0:96 offset1:164
	s_waitcnt lgkmcnt(7)
	v_fma_f32 v59, -v65, v58, v144
	v_fma_f32 v59, v64, v61, v59
	v_fma_f32 v58, v64, v58, v145
	v_fma_f32 v58, v65, v61, v58
	v_add_u32_e32 v60, 0x8000, v58
	v_add_u32_e32 v61, 0x8000, v59
	v_perm_b32 v60, v60, v61, s25
	v_fma_f32 v61, -v65, v58, v146
	v_fma_f32 v61, v64, v59, v61
	v_fma_f32 v58, v64, v58, v147
	v_fma_f32 v58, v65, v59, v58
	v_add_u32_e32 v59, 0x8000, v58
	v_add_u32_e32 v66, 0x8000, v61
	v_perm_b32 v59, v59, v66, s25
	v_add_u32_e32 v66, 0x2a00, v106
	ds_write2_b32 v66, v60, v59 offset0:104 offset1:172
	s_waitcnt lgkmcnt(7)
; DEVINL float bf2f(u16 h) { return __uint_as_float(((unsigned)h) << 16); }
; DEVINL f32x4 mfma16(bf16x8 a, bf16x8 b, f32x4 c) { return __builtin_amdgcn_mfma_f32_16x16x32_bf16(a, b, c, 0, 0, 0); }
; DEVINL void s5_seg(const Params& p, char* wsm, int rb, int ntok, int g, float& hr, float& hi, bool outp) {
;     ...
;       for (int t = 0; t < 16; ++t) bu[t] = *(const float2*)(BUs + t * 132 + 2 * lane);
; #pragma unroll
;       for (int t = 0; t < 16; ++t) {
;         float nr = ab.x * hr - ab.y * hi + bu[t].x;
;         float ni = ab.x * hi + ab.y * hr + bu[t].y;
;         hr = nr; hi = ni;
;         if (outp) *(unsigned*)(Hs + t * 136 + 2 * lane) = pack2(hr, hi);
;       }
;     } else {
;       for (int t = 0; t < nt; ++t) {
;         float2 bu = *(const float2*)(BUs + t * 132 + 2 * lane);
;         float nr = ab.x * hr - ab.y * hi + bu.x;
;         float ni = ab.x * hi + ab.y * hr + bu.y;
;         hr = nr; hi = ni;
;         if (outp) *(unsigned*)(Hs + t * 136 + 2 * lane) = pack2(hr, hi);
;       }
;     }
;     __builtin_amdgcn_wave_barrier();
;     asm volatile("s_waitcnt lgkmcnt(0)" ::: "memory");
;     if (outp) {
;       f32x4 y = f32x4{0, 0, 0, 0};
; #pragma unroll
;       for (int ks = 0; ks < 4; ++ks) {
;         bf16x8 ha = *(const bf16x8*)(Hs + (lane & 15) * 136 + ks * 32 + 8 * (lane >> 4));
;         y = mfma16(ha, cm[ks], y);
;       }
;       if (tk0 < nt) {
;         float yv[4];
; #pragma unroll
;         for (int j = 0; j < 4; ++j) yv[j] = geluf_(y[j] + dsk * bf2f(u_cur[j]));
;         store_pairs(yg, 512, rb + t0 + tk0, ucol, yv[0], yv[1], yv[2], yv[3]);
	v_fma_f32 v59, -v65, v58, v148
	v_fma_f32 v59, v64, v61, v59
	v_fma_f32 v58, v64, v58, v149
	v_fma_f32 v58, v65, v61, v58
	v_add_u32_e32 v60, 0x8000, v58
	v_add_u32_e32 v61, 0x8000, v59
	v_perm_b32 v60, v60, v61, s25
	v_fma_f32 v61, -v65, v58, v150
	v_fma_f32 v61, v64, v59, v61
	v_fma_f32 v59, v65, v59, v151
	v_fma_f32 v59, v64, v58, v59
	v_add_u32_e32 v58, 0x8000, v59
	v_add_u32_e32 v66, 0x8000, v61
	v_perm_b32 v58, v58, v66, s25
	v_add_u32_e32 v66, 0x2c00, v106
	ds_write2_b32 v66, v60, v58 offset0:112 offset1:180
	s_waitcnt lgkmcnt(7)
	v_fma_f32 v58, -v65, v59, v152
	v_fma_f32 v58, v64, v61, v58
	v_fma_f32 v60, v64, v59, v153
	v_fma_f32 v60, v65, v61, v60
	v_add_u32_e32 v59, 0x8000, v60
	v_add_u32_e32 v61, 0x8000, v58
	v_perm_b32 v59, v59, v61, s25
	ds_write_b32 v106, v59 offset:12256
	ds_read_b64 v[66:67], v85 offset:7920
	v_pk_mul_f32 v[60:61], v[76:77], v[60:61] op_sel_hi:[1,0]
	v_min_i32_e32 v131, 16, v107
	v_pk_fma_f32 v[110:111], v[64:65], v[58:59], v[60:61] neg_lo:[0,0,1] neg_hi:[0,0,1]
	v_pk_fma_f32 v[58:59], v[64:65], v[58:59], v[60:61] op_sel_hi:[1,0,1]
	v_cmp_lt_i32_e64 s[36:37], v83, v131
	v_mov_b32_e32 v111, v59
	s_waitcnt lgkmcnt(0)
	v_pk_add_f32 v[66:67], v[66:67], v[110:111]
	s_nop 0
	v_add_u32_e32 v58, 0x8000, v67
	v_add_u32_e32 v59, 0x8000, v66
	v_perm_b32 v58, v58, v59, s25
	ds_write_b32 v106, v58 offset:12528
	s_waitcnt lgkmcnt(0)
	ds_read_b128 v[58:61], v86 offset:8448
	ds_read_b128 v[110:113], v86 offset:8512
	s_waitcnt lgkmcnt(1)
	v_mfma_f32_16x16x32_bf16 v[58:61], v[58:61], v[38:41], 0
	ds_read_b128 v[132:135], v86 offset:8576
	s_waitcnt lgkmcnt(1)
	v_mfma_f32_16x16x32_bf16 v[58:61], v[110:113], v[42:45], v[58:61]
	ds_read_b128 v[110:113], v86 offset:8640
	s_waitcnt lgkmcnt(1)
	v_mfma_f32_16x16x32_bf16 v[58:61], v[132:135], v[46:49], v[58:61]
	s_waitcnt lgkmcnt(0)
	v_mfma_f32_16x16x32_bf16 v[58:61], v[110:113], v[50:53], v[58:61]
	s_and_saveexec_b64 s[38:39], s[36:37]
	s_cbranch_execz .LS5C_nostore
	v_lshlrev_b32_e32 v108, 16, v108
	v_lshlrev_b32_e32 v90, 16, v90
	s_nop 3
	v_fma_f32 v58, v82, v108, v58
	v_lshlrev_b32_e32 v105, 16, v105
	v_fma_f32 v60, v82, v90, v60
	v_lshlrev_b32_e32 v88, 16, v88
	v_mul_f32_e32 v108, 0x3d372713, v58
	v_fma_f32 v59, v82, v105, v59
	v_mul_f32_e32 v90, 0x3d372713, v60
	v_fmac_f32_e32 v61, v82, v88
	v_mul_f32_e32 v108, v58, v108
	v_mul_f32_e32 v105, 0x3d372713, v59
	v_mul_f32_e32 v90, v60, v90
	v_mul_f32_e32 v88, 0x3d372713, v61
	v_fma_f32 v108, v58, v108, v58
	v_mul_f32_e32 v105, v59, v105
	v_fma_f32 v90, v60, v90, v60
	v_mul_f32_e32 v88, v61, v88
	v_mul_f32_e32 v108, 0x3f4c422a, v108
	v_fma_f32 v105, v59, v105, v59
	v_mul_f32_e32 v90, 0x3f4c422a, v90
	v_fma_f32 v88, v61, v88, v61
	v_add_f32_e32 v108, v108, v108
	v_mul_f32_e32 v105, 0x3f4c422a, v105
	v_add_f32_e32 v90, v90, v90
	v_mul_f32_e32 v88, 0x3f4c422a, v88
	v_mul_f32_e32 v108, 0x3fb8aa3b, v108
	v_add_f32_e32 v105, v105, v105
	v_mul_f32_e32 v90, 0x3fb8aa3b, v90
	v_add_f32_e32 v88, v88, v88
	v_exp_f32_e32 v108, v108
	v_mul_f32_e32 v105, 0x3fb8aa3b, v105
	v_exp_f32_e32 v90, v90
	v_mul_f32_e32 v88, 0x3fb8aa3b, v88
	v_exp_f32_e32 v105, v105
	v_exp_f32_e32 v88, v88
	v_add_f32_e32 v108, 1.0, v108
	v_add_f32_e32 v90, 1.0, v90
	v_rcp_f32_e32 v108, v108
	v_add_f32_e32 v105, 1.0, v105
	v_rcp_f32_e32 v90, v90
	v_add_f32_e32 v88, 1.0, v88
	v_rcp_f32_e32 v105, v105
	v_rcp_f32_e32 v88, v88
	v_fma_f32 v108, v108, -2.0, 1.0
	v_fma_f32 v90, v90, -2.0, 1.0
	v_mul_f32_e32 v58, 0.5, v58
	v_add_f32_e32 v108, 1.0, v108
	v_fma_f32 v105, v105, -2.0, 1.0
	v_mul_f32_e32 v60, 0.5, v60
	v_add_f32_e32 v90, 1.0, v90
	v_fma_f32 v88, v88, -2.0, 1.0
	v_mul_f32_e32 v58, v58, v108
	v_mul_f32_e32 v59, 0.5, v59
	v_add_f32_e32 v105, 1.0, v105
	v_mul_f32_e32 v60, v60, v90
	v_mul_f32_e32 v61, 0.5, v61
	v_add_f32_e32 v88, 1.0, v88
	v_mul_f32_e32 v59, v59, v105
	v_mul_f32_e32 v61, v61, v88
	v_mov_b32_dpp v88, v58 quad_perm:[1,0,3,2] row_mask:0xf bank_mask:0xf bound_ctrl:1
	v_mov_b32_dpp v105, v60 quad_perm:[1,0,3,2] row_mask:0xf bank_mask:0xf bound_ctrl:1
	v_cndmask_b32_e64 v60, v60, v88, s[34:35]
	v_cndmask_b32_e64 v58, v105, v58, s[34:35]
	v_mov_b32_dpp v90, v59 quad_perm:[1,0,3,2] row_mask:0xf bank_mask:0xf bound_ctrl:1
	v_mov_b32_dpp v108, v61 quad_perm:[1,0,3,2] row_mask:0xf bank_mask:0xf bound_ctrl:1
	v_add_u32_e32 v60, 0x8000, v60
	v_add_u32_e32 v58, 0x8000, v58
	v_perm_b32 v88, v60, v58, s25
	v_cndmask_b32_e64 v58, v61, v90, s[34:35]
	v_cndmask_b32_e64 v59, v108, v59, s[34:35]
	v_add_u32_e32 v58, 0x8000, v58
	v_add_u32_e32 v59, 0x8000, v59
	v_perm_b32 v90, v58, v59, s25
	v_add_u32_e32 v58, s66, v102
	v_ashrrev_i32_e32 v59, 31, v58
	v_lshlrev_b64 v[60:61], 10, v[58:59]
	v_add_u32_e32 v58, 1, v58
	v_ashrrev_i32_e32 v59, 31, v58
	v_lshlrev_b64 v[58:59], 10, v[58:59]
	v_lshl_add_u64 v[60:61], v[72:73], 0, v[60:61]
	v_lshl_add_u64 v[58:59], v[72:73], 0, v[58:59]
	global_store_dword v[60:61], v88, off
	global_store_dword v[58:59], v90, off
	s_branch .LBB0_520
